# ret_up and ret_out 128-tile GEMM k-loops: next k-substep fragment reads issued ahead into a second register set
# speedup vs baseline: 1.0046x; 1.0015x over previous
.LBB0_1407:
	s_setprio 2
	ds_read_b128 v[188:191], v134
	ds_read_b128 v[192:195], v135 offset:36864
	ds_read_b128 v[196:199], v135 offset:46080
	ds_read_b128 v[200:203], v134 offset:4608
	v_cndmask_b32_e64 v137, 0, 1, s[6:7]
	v_cmp_ne_u32_e64 s[0:1], 1, v137
	s_andn2_b64 vcc, exec, s[6:7]
	ds_read_b128 v[224:227], v134 offset:32
	ds_read_b128 v[228:231], v135 offset:36896
	ds_read_b128 v[232:235], v135 offset:46112
	ds_read_b128 v[236:239], v134 offset:4640
	s_waitcnt lgkmcnt(6)
	v_mfma_f32_32x32x16_bf16 v[50:65], v[188:191], v[192:195], v[50:65]
	s_waitcnt lgkmcnt(5)
	v_mfma_f32_32x32x16_bf16 v[34:49], v[188:191], v[196:199], v[34:49]
	s_waitcnt lgkmcnt(4)
	v_mfma_f32_32x32x16_bf16 v[0:15], v[200:203], v[192:195], v[0:15]
	v_mfma_f32_32x32x16_bf16 v[16:31], v[200:203], v[196:199], v[16:31]
	ds_read_b128 v[188:191], v134 offset:64
	ds_read_b128 v[192:195], v135 offset:36928
	ds_read_b128 v[196:199], v135 offset:46144
	ds_read_b128 v[200:203], v134 offset:4672
	s_waitcnt lgkmcnt(6)
	v_mfma_f32_32x32x16_bf16 v[50:65], v[224:227], v[228:231], v[50:65]
	s_waitcnt lgkmcnt(5)
	v_mfma_f32_32x32x16_bf16 v[34:49], v[224:227], v[232:235], v[34:49]
	s_waitcnt lgkmcnt(4)
	v_mfma_f32_32x32x16_bf16 v[0:15], v[236:239], v[228:231], v[0:15]
	v_mfma_f32_32x32x16_bf16 v[16:31], v[236:239], v[232:235], v[16:31]
	ds_read_b128 v[224:227], v134 offset:96
	ds_read_b128 v[228:231], v135 offset:36960
	ds_read_b128 v[232:235], v135 offset:46176
	ds_read_b128 v[236:239], v134 offset:4704
	s_waitcnt lgkmcnt(6)
	v_mfma_f32_32x32x16_bf16 v[50:65], v[188:191], v[192:195], v[50:65]
	s_waitcnt lgkmcnt(5)
	v_mfma_f32_32x32x16_bf16 v[34:49], v[188:191], v[196:199], v[34:49]
	s_waitcnt lgkmcnt(4)
	v_mfma_f32_32x32x16_bf16 v[0:15], v[200:203], v[192:195], v[0:15]
	v_mfma_f32_32x32x16_bf16 v[16:31], v[200:203], v[196:199], v[16:31]
	s_waitcnt lgkmcnt(2)
	v_mfma_f32_32x32x16_bf16 v[50:65], v[224:227], v[228:231], v[50:65]
	s_waitcnt lgkmcnt(1)
	v_mfma_f32_32x32x16_bf16 v[34:49], v[224:227], v[232:235], v[34:49]
	s_setprio 0
	s_waitcnt vmcnt(7)
	ds_write_b128 v136, v[98:101] offset:18432
	s_waitcnt vmcnt(3)
	ds_write_b128 v136, v[106:109] offset:55296
	ds_write_b128 v136, v[102:105] offset:23040
	s_waitcnt vmcnt(2)
	ds_write_b128 v136, v[118:121] offset:59904
	ds_write_b128 v136, v[110:113] offset:27648
	s_waitcnt vmcnt(1)
	ds_write_b128 v136, v[122:125] offset:64512
	ds_write_b128 v136, v[114:117] offset:32256
	s_waitcnt vmcnt(0)
	ds_write_b128 v32, v[126:129] offset:13824
	s_waitcnt lgkmcnt(0)
	s_barrier
	v_mfma_f32_32x32x16_bf16 v[0:15], v[236:239], v[228:231], v[0:15]
	v_mfma_f32_32x32x16_bf16 v[16:31], v[236:239], v[232:235], v[16:31]
	s_cbranch_vccnz .LBB0_1409
	global_load_dwordx4 v[98:101], v[130:131], off offset:384
	global_load_dwordx4 v[106:109], v[132:133], off offset:384
	global_load_dwordx4 v[102:105], v[150:151], off
	global_load_dwordx4 v[118:121], v[152:153], off
	global_load_dwordx4 v[110:113], v[154:155], off
	global_load_dwordx4 v[122:125], v[156:157], off
	global_load_dwordx4 v[114:117], v[158:159], off
	global_load_dwordx4 v[126:129], v[160:161], off
.LBB0_1409:
	s_setprio 2
	ds_read_b128 v[188:191], v134 offset:18432
	ds_read_b128 v[192:195], v135 offset:55296
	ds_read_b128 v[196:199], v135 offset:64512
	ds_read_b128 v[200:203], v134 offset:23040
	s_and_b64 vcc, exec, s[0:1]
	ds_read_b128 v[224:227], v134 offset:18464
	ds_read_b128 v[228:231], v135 offset:55328
	ds_read_b128 v[232:235], v135 offset:64544
	ds_read_b128 v[236:239], v134 offset:23072
	s_waitcnt lgkmcnt(6)
	v_mfma_f32_32x32x16_bf16 v[50:65], v[188:191], v[192:195], v[50:65]
	s_waitcnt lgkmcnt(5)
	v_mfma_f32_32x32x16_bf16 v[34:49], v[188:191], v[196:199], v[34:49]
	s_waitcnt lgkmcnt(4)
	v_mfma_f32_32x32x16_bf16 v[0:15], v[200:203], v[192:195], v[0:15]
	v_mfma_f32_32x32x16_bf16 v[16:31], v[200:203], v[196:199], v[16:31]
	ds_read_b128 v[188:191], v134 offset:18496
	ds_read_b128 v[192:195], v135 offset:55360
	ds_read_b128 v[196:199], v135 offset:64576
	ds_read_b128 v[200:203], v134 offset:23104
	s_waitcnt lgkmcnt(6)
	v_mfma_f32_32x32x16_bf16 v[50:65], v[224:227], v[228:231], v[50:65]
	s_waitcnt lgkmcnt(5)
	v_mfma_f32_32x32x16_bf16 v[34:49], v[224:227], v[232:235], v[34:49]
	s_waitcnt lgkmcnt(4)
	v_mfma_f32_32x32x16_bf16 v[0:15], v[236:239], v[228:231], v[0:15]
	v_mfma_f32_32x32x16_bf16 v[16:31], v[236:239], v[232:235], v[16:31]
	ds_read_b128 v[224:227], v134 offset:18528
	ds_read_b128 v[228:231], v135 offset:55392
	ds_read_b128 v[232:235], v135 offset:64608
	ds_read_b128 v[236:239], v134 offset:23136
	s_waitcnt lgkmcnt(6)
	v_mfma_f32_32x32x16_bf16 v[50:65], v[188:191], v[192:195], v[50:65]
	s_waitcnt lgkmcnt(5)
	v_mfma_f32_32x32x16_bf16 v[34:49], v[188:191], v[196:199], v[34:49]
	s_waitcnt lgkmcnt(4)
	v_mfma_f32_32x32x16_bf16 v[0:15], v[200:203], v[192:195], v[0:15]
	v_mfma_f32_32x32x16_bf16 v[16:31], v[200:203], v[196:199], v[16:31]
	s_waitcnt lgkmcnt(2)
	v_mfma_f32_32x32x16_bf16 v[50:65], v[224:227], v[228:231], v[50:65]
	s_waitcnt lgkmcnt(1)
	v_mfma_f32_32x32x16_bf16 v[34:49], v[224:227], v[232:235], v[34:49]
	s_waitcnt lgkmcnt(0)
	v_mfma_f32_32x32x16_bf16 v[0:15], v[236:239], v[228:231], v[0:15]
	v_mfma_f32_32x32x16_bf16 v[16:31], v[236:239], v[232:235], v[16:31]
	s_setprio 0
	s_cbranch_vccnz .LBB0_1404
	ds_write_b128 v136, v[66:69]
	ds_write_b128 v136, v[70:73] offset:36864
	ds_write_b128 v136, v[74:77] offset:4608
	ds_write_b128 v136, v[78:81] offset:41472
	ds_write_b128 v136, v[82:85] offset:9216
	ds_write_b128 v136, v[86:89] offset:46080
	ds_write_b128 v136, v[90:93] offset:13824
	ds_write_b128 v136, v[94:97] offset:50688
	s_branch .LBB0_1404

.LBB0_1564:
	s_setprio 2
	ds_read_b128 v[188:191], v134
	ds_read_b128 v[192:195], v135 offset:36864
	ds_read_b128 v[196:199], v135 offset:46080
	ds_read_b128 v[200:203], v134 offset:4608
	v_cndmask_b32_e64 v137, 0, 1, s[8:9]
	v_cmp_ne_u32_e64 s[0:1], 1, v137
	s_andn2_b64 vcc, exec, s[8:9]
	ds_read_b128 v[224:227], v134 offset:32
	ds_read_b128 v[228:231], v135 offset:36896
	ds_read_b128 v[232:235], v135 offset:46112
	ds_read_b128 v[236:239], v134 offset:4640
	s_waitcnt lgkmcnt(6)
	v_mfma_f32_32x32x16_bf16 v[50:65], v[188:191], v[192:195], v[50:65]
	s_waitcnt lgkmcnt(5)
	v_mfma_f32_32x32x16_bf16 v[34:49], v[188:191], v[196:199], v[34:49]
	s_waitcnt lgkmcnt(4)
	v_mfma_f32_32x32x16_bf16 v[16:31], v[200:203], v[192:195], v[16:31]
	v_mfma_f32_32x32x16_bf16 v[0:15], v[200:203], v[196:199], v[0:15]
	ds_read_b128 v[188:191], v134 offset:64
	ds_read_b128 v[192:195], v135 offset:36928
	ds_read_b128 v[196:199], v135 offset:46144
	ds_read_b128 v[200:203], v134 offset:4672
	s_waitcnt lgkmcnt(6)
	v_mfma_f32_32x32x16_bf16 v[50:65], v[224:227], v[228:231], v[50:65]
	s_waitcnt lgkmcnt(5)
	v_mfma_f32_32x32x16_bf16 v[34:49], v[224:227], v[232:235], v[34:49]
	s_waitcnt lgkmcnt(4)
	v_mfma_f32_32x32x16_bf16 v[16:31], v[236:239], v[228:231], v[16:31]
	v_mfma_f32_32x32x16_bf16 v[0:15], v[236:239], v[232:235], v[0:15]
	ds_read_b128 v[224:227], v134 offset:96
	ds_read_b128 v[228:231], v135 offset:36960
	ds_read_b128 v[232:235], v135 offset:46176
	ds_read_b128 v[236:239], v134 offset:4704
	s_waitcnt lgkmcnt(6)
	v_mfma_f32_32x32x16_bf16 v[50:65], v[188:191], v[192:195], v[50:65]
	s_waitcnt lgkmcnt(5)
	v_mfma_f32_32x32x16_bf16 v[34:49], v[188:191], v[196:199], v[34:49]
	s_waitcnt lgkmcnt(4)
	v_mfma_f32_32x32x16_bf16 v[16:31], v[200:203], v[192:195], v[16:31]
	v_mfma_f32_32x32x16_bf16 v[0:15], v[200:203], v[196:199], v[0:15]
	s_waitcnt lgkmcnt(2)
	v_mfma_f32_32x32x16_bf16 v[50:65], v[224:227], v[228:231], v[50:65]
	s_waitcnt lgkmcnt(1)
	v_mfma_f32_32x32x16_bf16 v[34:49], v[224:227], v[232:235], v[34:49]
	s_setprio 0
	s_waitcnt vmcnt(7)
	ds_write_b128 v136, v[94:97] offset:18432
	s_waitcnt vmcnt(6)
	ds_write_b128 v136, v[98:101] offset:55296
	s_waitcnt vmcnt(5)
	ds_write_b128 v136, v[102:105] offset:23040
	s_waitcnt vmcnt(4)
	ds_write_b128 v136, v[110:113] offset:59904
	s_waitcnt vmcnt(3)
	ds_write_b128 v136, v[114:117] offset:27648
	s_waitcnt vmcnt(2)
	ds_write_b128 v136, v[118:121] offset:64512
	s_waitcnt vmcnt(1)
	ds_write_b128 v136, v[122:125] offset:32256
	s_waitcnt vmcnt(0)
	ds_write_b128 v32, v[126:129] offset:13824
	s_waitcnt lgkmcnt(0)
	s_barrier
	v_mfma_f32_32x32x16_bf16 v[16:31], v[236:239], v[228:231], v[16:31]
	v_mfma_f32_32x32x16_bf16 v[0:15], v[236:239], v[232:235], v[0:15]
	s_cbranch_vccnz .LBB0_1566
	global_load_dwordx4 v[94:97], v[130:131], off offset:384
	global_load_dwordx4 v[98:101], v[132:133], off offset:384
	global_load_dwordx4 v[102:105], v[150:151], off
	global_load_dwordx4 v[110:113], v[152:153], off
	global_load_dwordx4 v[114:117], v[154:155], off
	global_load_dwordx4 v[118:121], v[156:157], off
	global_load_dwordx4 v[122:125], v[158:159], off
	global_load_dwordx4 v[126:129], v[160:161], off
.LBB0_1566:
	s_setprio 2
	ds_read_b128 v[188:191], v134 offset:18432
	ds_read_b128 v[192:195], v135 offset:55296
	ds_read_b128 v[196:199], v135 offset:64512
	ds_read_b128 v[200:203], v134 offset:23040
	s_and_b64 vcc, exec, s[0:1]
	ds_read_b128 v[224:227], v134 offset:18464
	ds_read_b128 v[228:231], v135 offset:55328
	ds_read_b128 v[232:235], v135 offset:64544
	ds_read_b128 v[236:239], v134 offset:23072
	s_waitcnt lgkmcnt(6)
	v_mfma_f32_32x32x16_bf16 v[50:65], v[188:191], v[192:195], v[50:65]
	s_waitcnt lgkmcnt(5)
	v_mfma_f32_32x32x16_bf16 v[34:49], v[188:191], v[196:199], v[34:49]
	s_waitcnt lgkmcnt(4)
	v_mfma_f32_32x32x16_bf16 v[16:31], v[200:203], v[192:195], v[16:31]
	v_mfma_f32_32x32x16_bf16 v[0:15], v[200:203], v[196:199], v[0:15]
	ds_read_b128 v[188:191], v134 offset:18496
	ds_read_b128 v[192:195], v135 offset:55360
	ds_read_b128 v[196:199], v135 offset:64576
	ds_read_b128 v[200:203], v134 offset:23104
	s_waitcnt lgkmcnt(6)
	v_mfma_f32_32x32x16_bf16 v[50:65], v[224:227], v[228:231], v[50:65]
	s_waitcnt lgkmcnt(5)
	v_mfma_f32_32x32x16_bf16 v[34:49], v[224:227], v[232:235], v[34:49]
	s_waitcnt lgkmcnt(4)
	v_mfma_f32_32x32x16_bf16 v[16:31], v[236:239], v[228:231], v[16:31]
	v_mfma_f32_32x32x16_bf16 v[0:15], v[236:239], v[232:235], v[0:15]
	ds_read_b128 v[224:227], v134 offset:18528
	ds_read_b128 v[228:231], v135 offset:55392
	ds_read_b128 v[232:235], v135 offset:64608
	ds_read_b128 v[236:239], v134 offset:23136
	s_waitcnt lgkmcnt(6)
	v_mfma_f32_32x32x16_bf16 v[50:65], v[188:191], v[192:195], v[50:65]
	s_waitcnt lgkmcnt(5)
	v_mfma_f32_32x32x16_bf16 v[34:49], v[188:191], v[196:199], v[34:49]
	s_waitcnt lgkmcnt(4)
	v_mfma_f32_32x32x16_bf16 v[16:31], v[200:203], v[192:195], v[16:31]
	v_mfma_f32_32x32x16_bf16 v[0:15], v[200:203], v[196:199], v[0:15]
	s_waitcnt lgkmcnt(2)
	v_mfma_f32_32x32x16_bf16 v[50:65], v[224:227], v[228:231], v[50:65]
	s_waitcnt lgkmcnt(1)
	v_mfma_f32_32x32x16_bf16 v[34:49], v[224:227], v[232:235], v[34:49]
	s_waitcnt lgkmcnt(0)
	v_mfma_f32_32x32x16_bf16 v[16:31], v[236:239], v[228:231], v[16:31]
	v_mfma_f32_32x32x16_bf16 v[0:15], v[236:239], v[232:235], v[0:15]
	s_setprio 0
	s_cbranch_vccnz .LBB0_1561
	ds_write_b128 v136, v[66:69]
	ds_write_b128 v136, v[70:73] offset:36864
	ds_write_b128 v136, v[74:77] offset:4608
	ds_write_b128 v136, v[78:81] offset:41472
	ds_write_b128 v136, v[82:85] offset:9216
	ds_write_b128 v136, v[86:89] offset:46080
	ds_write_b128 v136, v[90:93] offset:13824
	ds_write_b128 v136, v[106:109] offset:50688
	s_branch .LBB0_1561
